# v59 + grid barrier: non-leader workgroups also poll the TOP arrival counter directly (no per-XCD generation hop)
# speedup vs baseline: 1.0066x; 1.0066x over previous
; __device__ __forceinline__ unsigned xb_ld(unsigned* p)              { return __hip_atomic_load(p, __ATOMIC_RELAXED, __HIP_MEMORY_SCOPE_AGENT); }
; __device__ __forceinline__ unsigned xb_add(unsigned* p, unsigned v) { return __hip_atomic_fetch_add(p, v, __ATOMIC_RELAXED, __HIP_MEMORY_SCOPE_AGENT); }
; #define XB_SPIN(cond, bar) do { unsigned _sp = 0; while (cond) { __builtin_amdgcn_s_sleep(1); \
;     if ((++_sp & 255u) == 0u) { if (xb_ld(&(bar)[XB_TMO])) break; if (_sp > XB_SPIN_CAP) { atomicAdd(&(bar)[XB_TMO], 1u); break; } } } } while (0)
; __device__ __forceinline__ void xcd_barrier(const XcdBarrier& b) {
;     ...
;         const unsigned old = xb_add(&bar[XB_XSUB(b.x)], 1u);
;         const unsigned gen = old / nloc;
;         if (old + 1u == (gen + 1u) * nloc) {
;             __builtin_amdgcn_fence(__ATOMIC_RELEASE, "agent");
;             asm volatile("s_waitcnt vmcnt(0)" ::: "memory");
;             const unsigned og = xb_add(&bar[XB_TOP], 1u);
;             const unsigned tg = og / nx;
;             if (og + 1u == (tg + 1u) * nx) xb_add(&bar[XB_TOPGEN], 1u);
;             else XB_SPIN(xb_ld(&bar[XB_TOPGEN]) == tg, bar);
;             __builtin_amdgcn_fence(__ATOMIC_ACQUIRE, "agent");
;             xb_add(&bar[XB_XGEN(b.x)], 1u);
;             asm volatile("s_waitcnt vmcnt(0)" ::: "memory");
;         } else {
;             XB_SPIN(xb_ld(&bar[XB_XGEN(b.x)]) == gen, bar);
;             __builtin_amdgcn_fence(__ATOMIC_ACQUIRE, "agent");
;             asm volatile("s_waitcnt vmcnt(0)" ::: "memory");
;         }
.LBB0_576:
	s_or_b64 exec, exec, s[10:11]
	v_cvt_f32_u32_e32 v5, v3
	s_waitcnt vmcnt(0)
	v_readfirstlane_b32 s5, v4
	v_sub_u32_e32 v4, 0, v3
	v_rcp_iflag_f32_e32 v5, v5
	v_add_u32_e32 v6, s5, v1
	v_mul_f32_e32 v5, 0x4f7ffffe, v5
	v_cvt_u32_f32_e32 v5, v5
	v_mul_lo_u32 v1, v4, v5
	v_mul_hi_u32 v1, v5, v1
	v_add_u32_e32 v1, v5, v1
	v_mul_hi_u32 v1, v6, v1
	v_mul_lo_u32 v4, v1, v3
	v_sub_u32_e32 v4, v6, v4
	v_add_u32_e32 v5, 1, v1
	v_cmp_ge_u32_e32 vcc, v4, v3
	s_nop 1
	v_cndmask_b32_e32 v1, v1, v5, vcc
	v_sub_u32_e32 v5, v4, v3
	v_cndmask_b32_e32 v4, v4, v5, vcc
	v_add_u32_e32 v5, 1, v1
	v_cmp_ge_u32_e32 vcc, v4, v3
	v_add_u32_e32 v4, 1, v6
	s_nop 0
	v_cndmask_b32_e32 v1, v1, v5, vcc
	v_mul_lo_u32 v5, v3, v1
	v_add_u32_e32 v3, v5, v3
	v_cmp_ne_u32_e32 vcc, v4, v3
	s_and_saveexec_b64 s[10:11], vcc
	s_xor_b64 s[10:11], exec, s[10:11]
	s_cbranch_execz .LBB0_590
	v_readlane_b32 s12, v254, 15
	v_readlane_b32 s13, v254, 16
	s_waitcnt lgkmcnt(0)
	v_mad_u32_u24 v6, v1, v2, v2
	s_nop 3
	global_load_dword v2, v203, s[12:13] sc1
	s_waitcnt vmcnt(0)
	v_cmp_lt_u32_e32 vcc, v2, v6
	s_and_saveexec_b64 s[12:13], vcc
	s_cbranch_execz .LBB0_589
	s_mov_b32 s5, 1
	s_mov_b64 s[18:19], 0
	s_branch .LBB0_580

; __device__ __forceinline__ unsigned xb_ld(unsigned* p)              { return __hip_atomic_load(p, __ATOMIC_RELAXED, __HIP_MEMORY_SCOPE_AGENT); }
; __device__ __forceinline__ unsigned xb_add(unsigned* p, unsigned v) { return __hip_atomic_fetch_add(p, v, __ATOMIC_RELAXED, __HIP_MEMORY_SCOPE_AGENT); }
; #define XB_SPIN(cond, bar) do { unsigned _sp = 0; while (cond) { __builtin_amdgcn_s_sleep(1); \
;     if ((++_sp & 255u) == 0u) { if (xb_ld(&(bar)[XB_TMO])) break; if (_sp > XB_SPIN_CAP) { atomicAdd(&(bar)[XB_TMO], 1u); break; } } } } while (0)
; __device__ __forceinline__ void xcd_barrier(const XcdBarrier& b) {
;     ...
;         const unsigned old = xb_add(&bar[XB_XSUB(b.x)], 1u);
;         const unsigned gen = old / nloc;
;         if (old + 1u == (gen + 1u) * nloc) {
;             __builtin_amdgcn_fence(__ATOMIC_RELEASE, "agent");
;             asm volatile("s_waitcnt vmcnt(0)" ::: "memory");
;             const unsigned og = xb_add(&bar[XB_TOP], 1u);
;             const unsigned tg = og / nx;
;             if (og + 1u == (tg + 1u) * nx) xb_add(&bar[XB_TOPGEN], 1u);
;             else XB_SPIN(xb_ld(&bar[XB_TOPGEN]) == tg, bar);
;             __builtin_amdgcn_fence(__ATOMIC_ACQUIRE, "agent");
;             xb_add(&bar[XB_XGEN(b.x)], 1u);
;             asm volatile("s_waitcnt vmcnt(0)" ::: "memory");
;         } else {
;             XB_SPIN(xb_ld(&bar[XB_XGEN(b.x)]) == gen, bar);
;             __builtin_amdgcn_fence(__ATOMIC_ACQUIRE, "agent");
;             asm volatile("s_waitcnt vmcnt(0)" ::: "memory");
;         }
.LBB0_1946:
	s_or_b64 exec, exec, s[8:9]
	v_cvt_f32_u32_e32 v5, v3
	s_waitcnt vmcnt(0)
	v_readfirstlane_b32 s4, v4
	v_sub_u32_e32 v4, 0, v3
	v_rcp_iflag_f32_e32 v5, v5
	v_add_u32_e32 v6, s4, v1
	v_mul_f32_e32 v5, 0x4f7ffffe, v5
	v_cvt_u32_f32_e32 v5, v5
	v_mul_lo_u32 v1, v4, v5
	v_mul_hi_u32 v1, v5, v1
	v_add_u32_e32 v1, v5, v1
	v_mul_hi_u32 v1, v6, v1
	v_mul_lo_u32 v4, v1, v3
	v_sub_u32_e32 v4, v6, v4
	v_add_u32_e32 v5, 1, v1
	v_cmp_ge_u32_e32 vcc, v4, v3
	s_nop 1
	v_cndmask_b32_e32 v1, v1, v5, vcc
	v_sub_u32_e32 v5, v4, v3
	v_cndmask_b32_e32 v4, v4, v5, vcc
	v_add_u32_e32 v5, 1, v1
	v_cmp_ge_u32_e32 vcc, v4, v3
	v_add_u32_e32 v4, 1, v6
	s_nop 0
	v_cndmask_b32_e32 v1, v1, v5, vcc
	v_mul_lo_u32 v5, v3, v1
	v_add_u32_e32 v3, v5, v3
	v_cmp_ne_u32_e32 vcc, v4, v3
	s_and_saveexec_b64 s[4:5], vcc
	s_xor_b64 s[8:9], exec, s[4:5]
	s_cbranch_execz .LBB0_1960
	v_readlane_b32 s4, v254, 15
	v_readlane_b32 s5, v254, 16
	s_waitcnt lgkmcnt(0)
	v_mad_u32_u24 v6, v1, v2, v2
	s_nop 3
	global_load_dword v2, v203, s[4:5] sc1
	s_waitcnt vmcnt(0)
	v_cmp_lt_u32_e32 vcc, v2, v6
	s_and_saveexec_b64 s[10:11], vcc
	s_cbranch_execz .LBB0_1959
	s_mov_b32 s4, 1
	s_mov_b64 s[12:13], 0
	s_branch .LBB0_1950
